# P0 prep loop: LayerNorm gamma/beta read from LDS (filled once per workgroup) instead of 32 global loads + vmcnt(0) waits per iteration
# speedup vs baseline: 1.0598x; 1.0039x over previous
.LBB0_58:
	s_or_b64 exec, exec, s[0:1]
	v_lshlrev_b32_e32 v250, 4, v128
	global_load_dwordx4 v[244:247], v250, s[62:63]
	global_load_dwordx4 v[240:243], v250, s[64:65]
	v_add_u32_e32 v251, 0x20010, v250
	s_waitcnt vmcnt(0)
	ds_write_b128 v251, v[244:247]
	ds_write_b128 v251, v[240:243] offset:8192
	v_lshrrev_b32_e32 v2, 6, v128
	v_lshl_add_u32 v90, s33, 3, v2
	s_mov_b32 s45, 0x8000
	v_cmp_gt_i32_e32 vcc, s45, v90
	s_waitcnt lgkmcnt(0)
	s_barrier
	s_and_saveexec_b64 s[26:27], vcc
	s_cbranch_execz .LBB0_163
	v_and_b32_e32 v3, 63, v128
	v_lshlrev_b32_e32 v92, 3, v3
	v_lshlrev_b32_e32 v4, 4, v3
	v_cmp_eq_u32_e64 s[8:9], 0, v3
	v_and_b32_e32 v3, 16, v128
	v_and_b32_e32 v6, 3, v128
	v_cmp_eq_u32_e64 s[10:11], 0, v3
	v_and_b32_e32 v3, 8, v128
	v_cmp_eq_u32_e64 s[2:3], 0, v6
	v_and_b32_e32 v6, 32, v128
	v_cmp_eq_u32_e64 s[12:13], 0, v3
	v_and_b32_e32 v3, 4, v128
	v_mov_b32_e32 v93, 0
	v_cmp_eq_u32_e64 s[4:5], 0, v6
	v_cmp_ne_u32_e64 s[6:7], 0, v6
	v_lshlrev_b32_e32 v6, 18, v128
	v_cmp_eq_u32_e64 s[14:15], 0, v3
	v_mbcnt_lo_u32_b32 v3, -1, 0
	v_mov_b32_e32 v5, v93
	v_and_b32_e32 v94, 0xe00000, v6
	v_lshlrev_b32_e32 v6, 4, v128
	v_mbcnt_hi_u32_b32 v3, -1, v3
	v_and_b32_e32 v96, 0x70, v6
	v_lshl_add_u64 v[100:101], s[60:61], 0, v[4:5]
	v_lshl_add_u64 v[102:103], s[62:63], 0, v[4:5]
	v_lshl_add_u64 v[104:105], s[64:65], 0, v[4:5]
	v_and_b32_e32 v6, 60, v128
	v_mov_b32_e32 v7, v93
	v_and_b32_e32 v5, 64, v3
	v_lshl_add_u64 v[106:107], s[68:69], 0, v[6:7]
	v_add_u32_e32 v5, 64, v5
	v_xor_b32_e32 v7, 32, v3
	v_cmp_lt_i32_e32 vcc, v7, v5
	v_lshlrev_b32_e32 v2, 11, v2
	v_ashrrev_i32_e32 v91, 31, v90
	v_cndmask_b32_e32 v7, v3, v7, vcc
	v_lshlrev_b32_e32 v180, 2, v7
	v_xor_b32_e32 v7, 16, v3
	v_cmp_lt_i32_e32 vcc, v7, v5
	v_lshl_add_u32 v186, s33, 14, v2
	s_lshl_b32 s51, s84, 3
	v_cndmask_b32_e32 v7, v3, v7, vcc
	v_lshlrev_b32_e32 v181, 2, v7
	v_xor_b32_e32 v7, 8, v3
	v_cmp_lt_i32_e32 vcc, v7, v5
	s_mov_b64 s[20:21], 0x3ed00000
	s_lshl_b32 s28, s84, 4
	v_cndmask_b32_e32 v7, v3, v7, vcc
	v_lshlrev_b32_e32 v182, 2, v7
	v_xor_b32_e32 v7, 4, v3
	v_cmp_lt_i32_e32 vcc, v7, v5
	v_add_u32_e32 v1, 16, v4
	s_mov_b64 s[30:31], 0x1000
	v_cndmask_b32_e32 v7, v3, v7, vcc
	v_lshlrev_b32_e32 v183, 2, v7
	v_xor_b32_e32 v7, 2, v3
	v_cmp_lt_i32_e32 vcc, v7, v5
	s_mov_b64 s[0:1], 0x1400
	s_mov_b64 s[16:17], 0x1800
	v_cndmask_b32_e32 v7, v3, v7, vcc
	v_lshlrev_b32_e32 v184, 2, v7
	v_xor_b32_e32 v7, 1, v3
	v_cmp_lt_i32_e32 vcc, v7, v5
	s_mov_b64 s[18:19], 0x1c00
	s_ashr_i32 s29, s28, 31
	v_cndmask_b32_e32 v3, v3, v7, vcc
	v_lshlrev_b32_e32 v185, 2, v3
	v_lshlrev_b64 v[2:3], 6, v[90:91]
	v_or_b32_e32 v2, v2, v6
	v_lshl_add_u64 v[108:109], v[2:3], 0, s[20:21]
	v_add_u32_e32 v2, s51, v90
	v_ashrrev_i32_e32 v3, 31, v2
	v_lshlrev_b64 v[2:3], 6, v[2:3]
	v_or_b32_e32 v2, v2, v6
	v_lshl_add_u64 v[110:111], v[2:3], 0, s[20:21]
	v_lshlrev_b64 v[2:3], 13, v[90:91]
	v_or_b32_e32 v2, v2, v4
	v_lshlrev_b64 v[112:113], 12, v[90:91]
	v_lshl_add_u64 v[2:3], s[60:61], 0, v[2:3]
	v_mov_b32_e32 v97, v93
	v_add_u32_e32 v129, 0x15000, v1
	v_add_u32_e32 v139, 0x15400, v1
	v_mov_b32_e32 v95, v93
	v_or_b32_e32 v98, 0x1000000, v94
	v_mov_b32_e32 v99, v93
	s_lshl_b32 s53, s84, 15
	s_lshl_b64 s[34:35], s[28:29], 6
	v_or_b32_e32 v112, v112, v92
	s_lshl_b64 s[36:37], s[28:29], 12
	v_lshl_add_u64 v[114:115], v[2:3], 0, s[30:31]
	s_lshl_b64 s[38:39], s[28:29], 13
	s_mov_b64 s[40:41], 0
	s_mov_b32 s29, 0x800000
	s_movk_i32 s61, 0x1000
	s_movk_i32 s64, 0x4000
	s_movk_i32 s65, 0x3fff
	v_lshlrev_b32_e32 v116, 2, v4
	s_mov_b32 s66, 0xbfb8aa3b
	s_mov_b32 s67, 0x3f2aaaab
	s_mov_b32 s44, 0x3e9b6dac
	s_mov_b32 s50, 0x3f2aaada
	s_mov_b32 s52, 0x3f317218
	s_mov_b32 s60, 0xb102e308
	s_mov_b32 s68, 0x7f800000
	s_mov_b32 s69, 0x33800000
	s_mov_b32 s82, 0x42fe0000
	s_mov_b32 s83, 0x40c0c00
	s_movk_i32 s88, 0x7fff
	v_add_u32_e32 v91, 0x15800, v1
	v_add_u32_e32 v187, 0x15c00, v1
	v_add_u32_e32 v188, 0x16000, v1
	v_add_u32_e32 v189, 0x16400, v1
	v_add_u32_e32 v190, 0x16800, v1
	v_add_u32_e32 v191, 0x16c00, v1
	v_add_u32_e32 v192, 0x17000, v1
	v_add_u32_e32 v193, 0x17400, v1
	v_add_u32_e32 v194, 0x17800, v1
	v_add_u32_e32 v195, 0x17c00, v1
	v_add_u32_e32 v196, 0x18000, v1
	v_add_u32_e32 v197, 0x18400, v1
	v_add_u32_e32 v198, 0x18800, v1
	v_add_u32_e32 v199, 0x18c00, v1
	v_add_u32_e32 v200, 0x19000, v1
	v_add_u32_e32 v201, 0x19400, v1
	v_add_u32_e32 v202, 0x19800, v1
	v_add_u32_e32 v203, 0x19c00, v1
	v_add_u32_e32 v204, 0x1a000, v1
	v_add_u32_e32 v205, 0x1a400, v1
	v_add_u32_e32 v206, 0x1a800, v1
	v_add_u32_e32 v207, 0x1ac00, v1
	v_add_u32_e32 v208, 0x1b000, v1
	v_add_u32_e32 v209, 0x1b400, v1
	v_add_u32_e32 v210, 0x1b800, v1
	v_add_u32_e32 v211, 0x1bc00, v1
	v_add_u32_e32 v212, 0x1c000, v1
	v_add_u32_e32 v213, 0x1c400, v1
	v_add_u32_e32 v214, 0x1c800, v1
	v_add_u32_e32 v215, 0x1cc00, v1
	v_add_u32_e32 v216, 0x1d000, v1
	v_add_u32_e32 v217, 0x1d400, v1
	v_add_u32_e32 v218, 0x1d800, v1
	v_add_u32_e32 v219, 0x1dc00, v1
	v_add_u32_e32 v220, 0x1e000, v1
	v_add_u32_e32 v221, 0x1e400, v1
	v_add_u32_e32 v222, 0x1e800, v1
	v_add_u32_e32 v223, 0x1ec00, v1
	v_add_u32_e32 v224, 0x1f000, v1
	v_add_u32_e32 v225, 0x1f400, v1
	v_add_u32_e32 v226, 0x1f800, v1
	v_add_u32_e32 v227, 0x1fc00, v1
	v_mov_b32_e32 v228, 0x3727c5ac
	v_mov_b32_e32 v229, 0x7f800000
	v_mov_b32_e32 v233, 0x7fc00000
	v_mov_b32_e32 v254, 0xff800000
	v_lshl_add_u64 v[118:119], s[80:81], 0, v[92:93]
	v_lshl_add_u64 v[120:121], v[104:105], 0, s[30:31]
	v_lshl_add_u64 v[122:123], v[102:103], 0, s[30:31]
	v_lshl_add_u64 v[124:125], v[104:105], 0, s[0:1]
	v_lshl_add_u64 v[126:127], v[102:103], 0, s[0:1]
	v_lshl_add_u64 v[130:131], v[104:105], 0, s[16:17]
	v_lshl_add_u64 v[132:133], v[102:103], 0, s[16:17]
	v_lshl_add_u64 v[134:135], v[104:105], 0, s[18:19]
	v_lshl_add_u64 v[136:137], v[102:103], 0, s[18:19]
	v_mov_b32_e32 v138, 0x3ecc95a3
	v_add_u32_e32 v102, 0x20010, v4
	s_branch .LBB0_61

.LBB0_61:
	global_load_dwordx4 v[20:23], v[114:115], off offset:-2048
	global_load_dwordx4 v[24:27], v[114:115], off offset:-4096
	global_load_dwordx4 v[28:31], v[114:115], off offset:-3072
	global_load_dwordx4 v[36:39], v[114:115], off offset:-1024
	global_load_dwordx4 v[2:5], v[114:115], off offset:3072
	global_load_dwordx4 v[10:13], v[114:115], off offset:2048
	global_load_dwordx4 v[14:17], v[114:115], off offset:1024
	global_load_dwordx4 v[32:35], v[114:115], off
	v_add_u32_e32 v232, s51, v90
	v_cmp_gt_i32_e64 s[16:17], s45, v232
	v_lshl_add_u64 v[76:77], s[80:81], 0, v[112:113]
	s_waitcnt vmcnt(7)
	v_mov_b32_e32 v6, v21
	s_waitcnt vmcnt(6)
	v_mov_b32_e32 v8, v24
	s_waitcnt vmcnt(5)
	v_mov_b32_e32 v9, v28
	v_mov_b32_e32 v18, v25
	v_mov_b32_e32 v19, v29
	v_mov_b32_e32 v40, v26
	v_mov_b32_e32 v41, v30
	v_mov_b32_e32 v42, v27
	v_mov_b32_e32 v43, v31
	v_mov_b32_e32 v7, v22
	v_mov_b32_e32 v44, v20
	v_mov_b32_e32 v45, v23
	v_pk_add_f32 v[8:9], v[8:9], v[18:19]
	v_pk_add_f32 v[18:19], v[40:41], v[42:43]
	s_waitcnt vmcnt(4)
	v_mov_b32_e32 v46, v37
	v_mov_b32_e32 v48, v39
	s_waitcnt vmcnt(0)
	v_mov_b32_e32 v47, v32
	v_pk_add_f32 v[6:7], v[6:7], v[44:45]
	v_pk_add_f32 v[8:9], v[8:9], v[18:19]
	v_pk_add_f32 v[40:41], v[36:37], v[46:47]
	v_pk_add_f32 v[42:43], v[38:39], v[48:49]
	v_pk_add_f32 v[6:7], v[6:7], v[6:7] op_sel:[0,1] op_sel_hi:[1,0]
	v_add_f32_e32 v8, 0, v8
	v_mov_b32_e32 v41, v34
	v_mov_b32_e32 v43, v35
	v_mov_b32_e32 v7, v33
	v_add_f32_e32 v46, v8, v9
	v_mov_b32_e32 v56, v16
	v_mov_b32_e32 v50, v14
	v_mov_b32_e32 v51, v16
	v_mov_b32_e32 v16, v15
	v_pk_add_f32 v[40:41], v[40:41], v[42:43]
	v_pk_add_f32 v[6:7], v[46:47], v[6:7]
	v_mov_b32_e32 v52, v2
	v_mov_b32_e32 v53, v10
	v_mov_b32_e32 v54, v4
	v_mov_b32_e32 v55, v12
	v_pk_add_f32 v[48:49], v[50:51], v[16:17]
	v_pk_add_f32 v[6:7], v[6:7], v[40:41]
	v_mov_b32_e32 v4, v5
	v_mov_b32_e32 v5, v13
	v_pk_add_f32 v[44:45], v[52:53], v[10:11]
	v_pk_add_f32 v[12:13], v[54:55], v[12:13]
	v_pk_add_f32 v[18:19], v[48:49], v[48:49] op_sel:[0,1] op_sel_hi:[1,0]
	v_pk_add_f32 v[6:7], v[6:7], v[6:7] op_sel:[0,1] op_sel_hi:[1,0]
	v_pk_mov_b32 v[44:45], v[44:45], v[54:55] op_sel:[1,0]
	v_pk_mov_b32 v[12:13], v[12:13], v[4:5] op_sel:[1,0]
	v_mov_b32_e32 v19, v3
	v_mov_b32_e32 v7, v2
	v_pk_add_f32 v[12:13], v[44:45], v[12:13]
	v_pk_add_f32 v[6:7], v[6:7], v[18:19]
	v_mov_b32_e32 v57, v34
	v_pk_add_f32 v[6:7], v[6:7], v[12:13]
	s_nop 0
	v_add_f32_e32 v2, v6, v7
	ds_bpermute_b32 v6, v180, v2
	s_waitcnt lgkmcnt(0)
	v_add_f32_e32 v2, v2, v6
	ds_bpermute_b32 v6, v181, v2
	s_waitcnt lgkmcnt(0)
	v_add_f32_e32 v2, v2, v6
	ds_bpermute_b32 v6, v182, v2
	s_waitcnt lgkmcnt(0)
	v_add_f32_e32 v10, v2, v6
	ds_read_b128 v[44:47], v102 offset:0
	ds_read_b128 v[6:9], v102 offset:8192
	ds_bpermute_b32 v12, v183, v10
	v_mov_b32_e32 v2, v3
	v_mov_b32_e32 v3, v11
	v_mov_b32_e32 v11, v32
	s_waitcnt lgkmcnt(0)
	v_add_f32_e32 v13, v10, v12
	ds_bpermute_b32 v16, v184, v13
	v_mov_b32_e32 v10, v14
	v_mov_b32_e32 v14, v17
	v_mov_b32_e32 v12, v15
	v_mov_b32_e32 v15, v35
	s_waitcnt lgkmcnt(0)
	v_add_f32_e32 v16, v13, v16
	ds_bpermute_b32 v18, v185, v16
	v_mov_b32_e32 v13, v33
	s_waitcnt lgkmcnt(0)
	v_add_f32_e32 v17, v16, v18
	v_fmamk_f32 v33, v17, 0xba000000, v25
	v_fmamk_f32 v41, v17, 0xba000000, v29
	v_mul_f32_e32 v16, 0x3a000000, v17
	v_fmamk_f32 v32, v17, 0xba000000, v24
	v_fmamk_f32 v26, v17, 0xba000000, v26
	v_fmac_f32_e32 v27, 0xba000000, v17
	v_fmamk_f32 v40, v17, 0xba000000, v28
	v_fmamk_f32 v30, v17, 0xba000000, v30
	v_fmac_f32_e32 v31, 0xba000000, v17
	v_fmamk_f32 v80, v17, 0xba000000, v20
	v_fmamk_f32 v81, v17, 0xba000000, v21
	v_fmamk_f32 v22, v17, 0xba000000, v22
	v_fmac_f32_e32 v23, 0xba000000, v17
	v_fmamk_f32 v82, v17, 0xba000000, v36
	v_fmamk_f32 v83, v17, 0xba000000, v37
	v_fmamk_f32 v38, v17, 0xba000000, v38
	v_fmac_f32_e32 v39, 0xba000000, v17
	v_mul_f32_e32 v17, v33, v33
	v_mul_f32_e32 v18, v41, v41
	v_mul_f32_e32 v19, v81, v81
	v_pk_add_f32 v[48:49], v[10:11], v[16:17] op_sel_hi:[1,0] neg_lo:[0,1] neg_hi:[0,1]
	v_pk_add_f32 v[50:51], v[12:13], v[16:17] op_sel_hi:[1,0] neg_lo:[0,1] neg_hi:[0,1]
	v_pk_add_f32 v[56:57], v[56:57], v[16:17] op_sel_hi:[1,0] neg_lo:[0,1] neg_hi:[0,1]
	v_pk_add_f32 v[78:79], v[14:15], v[16:17] op_sel_hi:[1,0] neg_lo:[0,1] neg_hi:[0,1]
	v_pk_add_f32 v[42:43], v[52:53], v[16:17] op_sel_hi:[1,0] neg_lo:[0,1] neg_hi:[0,1]
	v_pk_add_f32 v[70:71], v[2:3], v[16:17] op_sel_hi:[1,0] neg_lo:[0,1] neg_hi:[0,1]
	v_pk_add_f32 v[72:73], v[54:55], v[16:17] op_sel_hi:[1,0] neg_lo:[0,1] neg_hi:[0,1]
	v_pk_add_f32 v[74:75], v[4:5], v[16:17] op_sel_hi:[1,0] neg_lo:[0,1] neg_hi:[0,1]
	v_fmac_f32_e32 v17, v32, v32
	v_fmac_f32_e32 v18, v40, v40
	v_mul_f32_e32 v20, v83, v83
	v_fmac_f32_e32 v19, v80, v80
	v_fmac_f32_e32 v17, v26, v26
	v_fmac_f32_e32 v18, v30, v30
	v_fmac_f32_e32 v20, v82, v82
	v_pk_mul_f32 v[2:3], v[50:51], v[50:51]
	v_fmac_f32_e32 v19, v22, v22
	v_fmac_f32_e32 v17, v27, v27
	v_fmac_f32_e32 v18, v31, v31
	v_fmac_f32_e32 v20, v38, v38
	v_pk_fma_f32 v[2:3], v[48:49], v[48:49], v[2:3]
	v_fmac_f32_e32 v19, v23, v23
	v_add_f32_e32 v10, v17, v18
	v_pk_mul_f32 v[4:5], v[70:71], v[70:71]
	v_fmac_f32_e32 v20, v39, v39
	v_pk_fma_f32 v[2:3], v[56:57], v[56:57], v[2:3]
	v_add_f32_e32 v10, v19, v10
	v_pk_fma_f32 v[4:5], v[42:43], v[42:43], v[4:5]
	v_pk_fma_f32 v[2:3], v[78:79], v[78:79], v[2:3]
	v_add_f32_e32 v10, v20, v10
	v_pk_fma_f32 v[4:5], v[72:73], v[72:73], v[4:5]
	v_add_f32_e32 v3, v3, v10
	v_pk_fma_f32 v[4:5], v[74:75], v[74:75], v[4:5]
	v_add_f32_e32 v2, v2, v3
	v_add_f32_e32 v2, v5, v2
	v_add_f32_e32 v2, v4, v2
	ds_bpermute_b32 v3, v180, v2
	v_cndmask_b32_e64 v24, v90, v232, s[16:17]
	v_ashrrev_i32_e32 v25, 31, v24
	s_waitcnt lgkmcnt(0)
	v_add_f32_e32 v2, v2, v3
	ds_bpermute_b32 v3, v181, v2
	s_waitcnt lgkmcnt(0)
	v_add_f32_e32 v2, v2, v3
	ds_bpermute_b32 v3, v182, v2
	s_waitcnt lgkmcnt(0)
	v_add_f32_e32 v4, v2, v3
	ds_bpermute_b32 v5, v183, v4
	v_lshlrev_b64 v[2:3], 13, v[24:25]
	v_lshl_add_u64 v[28:29], v[100:101], 0, v[2:3]
	v_lshlrev_b64 v[24:25], 12, v[24:25]
	v_lshl_add_u64 v[24:25], v[118:119], 0, v[24:25]
	s_waitcnt lgkmcnt(0)
	v_add_f32_e32 v34, v4, v5
	ds_bpermute_b32 v35, v184, v34
	global_load_dwordx4 v[10:13], v[28:29], off offset:2048
	global_load_dwordx4 v[2:5], v[28:29], off offset:3072
	global_load_dwordx4 v[18:21], v[28:29], off
	global_load_dwordx4 v[14:17], v[28:29], off offset:1024
	v_add_co_u32_e32 v28, vcc, s61, v28
	s_waitcnt lgkmcnt(0)
	v_add_f32_e32 v34, v34, v35
	ds_bpermute_b32 v35, v185, v34
	v_addc_co_u32_e32 v29, vcc, 0, v29, vcc
	global_load_dwordx4 v[52:55], v[28:29], off offset:2048
	global_load_dwordx4 v[58:61], v[28:29], off offset:3072
	global_load_dwordx4 v[62:65], v[28:29], off
	global_load_dwordx4 v[66:69], v[28:29], off offset:1024
	s_waitcnt lgkmcnt(0)
	v_add_f32_e32 v34, v34, v35
	v_fmamk_f32 v34, v34, 0x3a000000, v228
	v_mul_f32_e32 v35, 0x4b800000, v34
	v_cmp_gt_f32_e32 vcc, s29, v34
	s_waitcnt vmcnt(3)
	s_waitcnt lgkmcnt(0)
	v_mov_b32_e32 v175, v55
	v_cndmask_b32_e32 v34, v34, v35, vcc
	v_rsq_f32_e32 v34, v34
	s_waitcnt vmcnt(2)
	v_mov_b32_e32 v174, v61
	v_mov_b32_e32 v61, v54
	v_pk_add_f32 v[176:177], v[60:61], v[54:55]
	v_mul_f32_e32 v28, 0x45800000, v34
	v_cndmask_b32_e32 v92, v34, v28, vcc
	v_mul_f32_e32 v28, v32, v92
	v_mul_f32_e32 v29, v33, v92
	v_mul_f32_e32 v26, v26, v92
	v_mul_f32_e32 v27, v27, v92
	v_fma_f32 v143, v46, v26, v8
	v_fma_f32 v141, v47, v27, v9
	v_fma_f32 v144, v44, v28, v6
	v_fmac_f32_e32 v7, v45, v29
	v_cvt_pk_bf16_f32 v8, v144, v7
	v_cvt_pk_bf16_f32 v9, v143, v141
	global_store_dwordx2 v[76:77], v[8:9], off
	ds_read_b128 v[26:29], v102 offset:9216
	ds_read_b128 v[32:35], v102 offset:1024
	v_mul_f32_e32 v6, v31, v92
	v_mul_f32_e32 v8, v40, v92
	v_mul_f32_e32 v9, v41, v92
	v_mul_f32_e32 v30, v30, v92
	v_mul_f32_e32 v22, v22, v92
	v_mov_b32_e32 v88, v58
	v_mov_b32_e32 v89, v52
	s_waitcnt vmcnt(2)
	v_mov_b32_e32 v87, v62
	v_pk_mov_b32 v[176:177], v[176:177], v[174:175] op_sel:[1,0]
	v_mul_f32_e32 v42, v42, v92
	s_waitcnt vmcnt(1)
	s_waitcnt lgkmcnt(0)
	v_fma_f32 v148, v32, v8, v26
	v_fma_f32 v151, v33, v9, v27
	v_fma_f32 v147, v34, v30, v28
	v_fmac_f32_e32 v29, v35, v6
	v_cvt_pk_bf16_f32 v8, v148, v151
	v_cvt_pk_bf16_f32 v9, v147, v29
	global_store_dwordx2 v[76:77], v[8:9], off offset:512
	ds_read_b128 v[30:33], v102 offset:10240
	ds_read_b128 v[34:37], v102 offset:2048
	v_mul_f32_e32 v6, v23, v92
	v_mul_f32_e32 v8, v80, v92
	v_mul_f32_e32 v9, v81, v92
	v_mov_b32_e32 v23, v15
	v_mov_b32_e32 v26, v20
	v_mov_b32_e32 v27, v16
	v_mov_b32_e32 v28, v5
	v_pk_add_f32 v[84:85], v[4:5], v[28:29]
	v_mul_f32_e32 v28, v43, v92
	v_mov_b32_e32 v85, v65
	v_mul_f32_e32 v43, v70, v92
	s_waitcnt lgkmcnt(0)
	v_fmac_f32_e32 v33, v6, v37
	v_fma_f32 v152, v8, v34, v30
	v_fma_f32 v155, v9, v35, v31
	v_fma_f32 v31, v22, v36, v32
	v_cvt_pk_bf16_f32 v8, v152, v155
	v_cvt_pk_bf16_f32 v9, v31, v33
	global_store_dwordx2 v[76:77], v[8:9], off offset:1024
	ds_read_b128 v[34:37], v102 offset:11264
	ds_read_b128 v[44:47], v102 offset:3072
	v_mul_f32_e32 v6, v39, v92
	v_mul_f32_e32 v8, v82, v92
	v_mul_f32_e32 v9, v83, v92
	v_mul_f32_e32 v22, v38, v92
	v_mul_f32_e32 v30, v71, v92
	v_mul_f32_e32 v32, v73, v92
	s_waitcnt lgkmcnt(0)
	v_fmac_f32_e32 v37, v6, v47
	v_fma_f32 v156, v8, v44, v34
	v_fma_f32 v159, v9, v45, v35
	v_fma_f32 v35, v22, v46, v36
	v_cvt_pk_bf16_f32 v8, v156, v159
	v_cvt_pk_bf16_f32 v9, v35, v37
	global_store_dwordx2 v[76:77], v[8:9], off offset:1536
	ds_read_b128 v[38:41], v102 offset:12288
	ds_read_b128 v[44:47], v102 offset:4096
	v_mul_f32_e32 v6, v79, v92
	v_mul_f32_e32 v8, v49, v92
	v_mul_f32_e32 v9, v51, v92
	v_mul_f32_e32 v22, v57, v92
	v_mov_b32_e32 v57, v12
	s_waitcnt lgkmcnt(0)
	v_fmac_f32_e32 v41, v6, v47
	v_fma_f32 v160, v8, v44, v38
	v_fma_f32 v163, v9, v45, v39
	v_fma_f32 v39, v22, v46, v40
	v_cvt_pk_bf16_f32 v8, v160, v163
	v_cvt_pk_bf16_f32 v9, v39, v41
	global_store_dwordx2 v[76:77], v[8:9], off offset:2048
	ds_read_b128 v[44:47], v102 offset:13312
	ds_read_b128 v[80:83], v102 offset:5120
	v_mul_f32_e32 v6, v48, v92
	v_mul_f32_e32 v8, v50, v92
	v_mul_f32_e32 v9, v56, v92
	v_mul_f32_e32 v22, v78, v92
	v_mov_b32_e32 v56, v11
	s_waitcnt lgkmcnt(0)
	v_fmac_f32_e32 v47, v22, v83
	v_fma_f32 v166, v6, v80, v44
	v_fma_f32 v169, v8, v81, v45
	v_fma_f32 v165, v9, v82, v46
	v_cvt_pk_bf16_f32 v8, v166, v169
	v_cvt_pk_bf16_f32 v9, v165, v47
	global_store_dwordx2 v[76:77], v[8:9], off offset:2560
	ds_read_b128 v[48:51], v102 offset:14336
	ds_read_b128 v[78:81], v102 offset:6144
	v_mov_b32_e32 v8, v18
	v_mov_b32_e32 v9, v14
	v_mov_b32_e32 v22, v19
	v_mov_b32_e32 v44, v21
	v_mov_b32_e32 v45, v17
	v_pk_add_f32 v[8:9], v[8:9], v[22:23]
	v_pk_add_f32 v[22:23], v[26:27], v[44:45]
	v_mov_b32_e32 v82, v10
	v_mov_b32_e32 v83, v13
	v_mov_b32_e32 v6, v3
	v_pk_add_f32 v[8:9], v[8:9], v[22:23]
	v_pk_add_f32 v[26:27], v[56:57], v[82:83]
	v_pk_add_f32 v[56:57], v[2:3], v[6:7]
	v_add_f32_e32 v6, 0, v8
	v_mul_f32_e32 v8, v75, v92
	v_mov_b32_e32 v57, v64
	v_pk_add_f32 v[84:85], v[56:57], v[84:85]
	v_pk_add_f32 v[26:27], v[26:27], v[26:27] op_sel:[0,1] op_sel_hi:[1,0]
	v_pk_add_f32 v[22:23], v[88:89], v[52:53]
	v_mov_b32_e32 v27, v63
	v_pk_mov_b32 v[22:23], v[22:23], v[60:61] op_sel:[1,0]
	v_add_f32_e32 v86, v6, v9
	v_mov_b32_e32 v44, v66
	v_mov_b32_e32 v45, v68
	v_mov_b32_e32 v82, v68
	v_mov_b32_e32 v68, v67
	v_pk_add_f32 v[44:45], v[44:45], v[68:69]
	v_mov_b32_e32 v52, v59
	v_pk_add_f32 v[44:45], v[44:45], v[44:45] op_sel:[0,1] op_sel_hi:[1,0]
	v_mov_b32_e32 v83, v64
	v_mov_b32_e32 v45, v59
	s_waitcnt lgkmcnt(0)
	v_fmac_f32_e32 v51, v8, v81
	v_fma_f32 v170, v28, v78, v48
	v_fma_f32 v173, v30, v79, v49
	v_fma_f32 v49, v32, v80, v50
	v_cvt_pk_bf16_f32 v54, v170, v173
	v_cvt_pk_bf16_f32 v55, v49, v51
	global_store_dwordx2 v[76:77], v[54:55], off offset:3072
	ds_read_b128 v[54:57], v102 offset:15360
	s_nop 0
	ds_read_b128 v[78:81], v102 offset:7168
	v_pk_add_f32 v[8:9], v[22:23], v[176:177]
	v_pk_add_f32 v[22:23], v[86:87], v[26:27]
	v_mul_f32_e32 v50, v72, v92
	v_pk_add_f32 v[22:23], v[22:23], v[84:85]
	s_waitcnt lgkmcnt(0)
	v_fma_f32 v176, v42, v78, v54
	v_pk_add_f32 v[22:23], v[22:23], v[22:23] op_sel:[0,1] op_sel_hi:[1,0]
	v_fma_f32 v179, v43, v79, v55
	v_mov_b32_e32 v23, v58
	v_pk_add_f32 v[22:23], v[22:23], v[44:45]
	v_cvt_pk_bf16_f32 v42, v176, v179
	s_nop 0
	v_pk_add_f32 v[8:9], v[22:23], v[8:9]
	v_mov_b32_e32 v22, v67
	v_add_f32_e32 v6, v8, v9
	ds_bpermute_b32 v8, v180, v6
	v_mov_b32_e32 v23, v63
	v_mov_b32_e32 v67, v65
	s_waitcnt lgkmcnt(0)
	v_add_f32_e32 v6, v6, v8
	ds_bpermute_b32 v8, v181, v6
	s_waitcnt lgkmcnt(0)
	v_add_f32_e32 v6, v6, v8
	ds_bpermute_b32 v8, v182, v6
	s_waitcnt lgkmcnt(0)
	v_add_f32_e32 v6, v6, v8
	ds_bpermute_b32 v9, v183, v6
	v_mov_b32_e32 v8, v66
	v_mov_b32_e32 v66, v69
	s_waitcnt lgkmcnt(0)
	v_add_f32_e32 v6, v6, v9
	ds_bpermute_b32 v26, v184, v6
	v_mov_b32_e32 v9, v62
	s_waitcnt lgkmcnt(0)
	v_add_f32_e32 v6, v6, v26
	ds_bpermute_b32 v26, v185, v6
	s_waitcnt lgkmcnt(0)
	v_add_f32_e32 v26, v6, v26
	v_mul_f32_e32 v6, 0x3a000000, v26
	v_fmamk_f32 v34, v26, 0xba000000, v10
	v_fmamk_f32 v30, v26, 0xba000000, v11
	v_pk_add_f32 v[10:11], v[52:53], v[6:7] op_sel_hi:[1,0] neg_lo:[0,1] neg_hi:[0,1]
	v_mul_f32_e32 v52, v74, v92
	v_fmamk_f32 v32, v26, 0xba000000, v2
	v_fmamk_f32 v28, v26, 0xba000000, v3
	v_pk_add_f32 v[2:3], v[174:175], v[6:7] op_sel_hi:[1,0] neg_lo:[0,1] neg_hi:[0,1]
	v_fmac_f32_e32 v57, v52, v81
	v_fma_f32 v175, v50, v80, v56
	v_cvt_pk_bf16_f32 v43, v175, v57
	global_store_dwordx2 v[76:77], v[42:43], off offset:3584
	v_pk_add_f32 v[44:45], v[8:9], v[6:7] op_sel_hi:[1,0] neg_lo:[0,1] neg_hi:[0,1]
	v_pk_add_f32 v[8:9], v[60:61], v[6:7] op_sel_hi:[1,0] neg_lo:[0,1] neg_hi:[0,1]
	ds_read_b128 v[52:55], v102 offset:0
	ds_read_b128 v[58:61], v102 offset:8192
	v_fmamk_f32 v48, v26, 0xba000000, v19
	v_fmamk_f32 v38, v26, 0xba000000, v15
	v_fmac_f32_e32 v21, 0xba000000, v26
	v_fmac_f32_e32 v17, 0xba000000, v26
	v_fmamk_f32 v46, v26, 0xba000000, v18
	v_fmamk_f32 v40, v26, 0xba000000, v14
	v_fmamk_f32 v20, v26, 0xba000000, v20
	v_fmamk_f32 v16, v26, 0xba000000, v16
	v_fmac_f32_e32 v13, 0xba000000, v26
	v_fmamk_f32 v12, v26, 0xba000000, v12
	v_fmac_f32_e32 v5, 0xba000000, v26
	v_fmamk_f32 v4, v26, 0xba000000, v4
	v_pk_add_f32 v[26:27], v[22:23], v[6:7] op_sel_hi:[1,0] neg_lo:[0,1] neg_hi:[0,1]
	v_pk_add_f32 v[22:23], v[82:83], v[6:7] op_sel_hi:[1,0] neg_lo:[0,1] neg_hi:[0,1]
	v_pk_add_f32 v[18:19], v[66:67], v[6:7] op_sel_hi:[1,0] neg_lo:[0,1] neg_hi:[0,1]
	v_pk_add_f32 v[14:15], v[88:89], v[6:7] op_sel_hi:[1,0] neg_lo:[0,1] neg_hi:[0,1]
	v_mul_f32_e32 v6, v48, v48
	v_mul_f32_e32 v36, v38, v38
	v_mul_f32_e32 v50, v30, v30
	v_fmac_f32_e32 v6, v46, v46
	v_fmac_f32_e32 v36, v40, v40
	v_mul_f32_e32 v56, v28, v28
	v_fmac_f32_e32 v50, v34, v34
	v_fmac_f32_e32 v6, v20, v20
	v_fmac_f32_e32 v36, v16, v16
	v_fmac_f32_e32 v56, v32, v32
	v_pk_mul_f32 v[42:43], v[26:27], v[26:27]
	v_fmac_f32_e32 v50, v12, v12
	v_fmac_f32_e32 v6, v21, v21
	v_fmac_f32_e32 v36, v17, v17
	v_fmac_f32_e32 v56, v4, v4
	v_pk_fma_f32 v[42:43], v[44:45], v[44:45], v[42:43]
	v_fmac_f32_e32 v50, v13, v13
	v_add_f32_e32 v6, v6, v36
	v_pk_mul_f32 v[62:63], v[10:11], v[10:11]
	v_fmac_f32_e32 v56, v5, v5
	v_pk_fma_f32 v[42:43], v[22:23], v[22:23], v[42:43]
	v_add_f32_e32 v6, v50, v6
	v_pk_fma_f32 v[62:63], v[14:15], v[14:15], v[62:63]
	v_pk_fma_f32 v[42:43], v[18:19], v[18:19], v[42:43]
	v_add_f32_e32 v6, v56, v6
	v_pk_fma_f32 v[62:63], v[8:9], v[8:9], v[62:63]
	v_add_f32_e32 v6, v43, v6
	v_pk_fma_f32 v[62:63], v[2:3], v[2:3], v[62:63]
	v_add_f32_e32 v6, v42, v6
	v_add_f32_e32 v6, v63, v6
	v_add_f32_e32 v6, v62, v6
	ds_bpermute_b32 v36, v180, v6
	s_waitcnt lgkmcnt(0)
	v_add_f32_e32 v6, v6, v36
	ds_bpermute_b32 v36, v181, v6
	s_waitcnt lgkmcnt(0)
	v_add_f32_e32 v6, v6, v36
	ds_bpermute_b32 v36, v182, v6
	s_waitcnt lgkmcnt(0)
	v_add_f32_e32 v6, v6, v36
	ds_bpermute_b32 v36, v183, v6
	s_waitcnt lgkmcnt(0)
	v_add_f32_e32 v6, v6, v36
	ds_bpermute_b32 v36, v184, v6
	s_waitcnt lgkmcnt(0)
	v_add_f32_e32 v6, v6, v36
	ds_bpermute_b32 v36, v185, v6
	s_waitcnt lgkmcnt(0)
	v_add_f32_e32 v6, v6, v36
	v_fmamk_f32 v6, v6, 0x3a000000, v228
	v_mul_f32_e32 v36, 0x4b800000, v6
	v_cmp_gt_f32_e32 vcc, s29, v6
	s_nop 1
	v_cndmask_b32_e32 v6, v6, v36, vcc
	v_rsq_f32_e32 v6, v6
	s_nop 0
	v_mul_f32_e32 v36, 0x45800000, v6
	v_cndmask_b32_e32 v36, v6, v36, vcc
	v_mul_f32_e32 v21, v21, v36
	v_mul_f32_e32 v6, v46, v36
	v_mul_f32_e32 v42, v48, v36
	v_mul_f32_e32 v20, v20, v36
	s_waitcnt lgkmcnt(0)
	v_fma_f32 v6, v52, v6, v58
	v_fma_f32 v145, v53, v42, v59
	v_fma_f32 v142, v54, v20, v60
	v_fmac_f32_e32 v61, v55, v21
	v_cvt_pk_bf16_f32 v20, v6, v145
	v_cvt_pk_bf16_f32 v21, v142, v61
	s_and_saveexec_b64 s[0:1], s[16:17]
	s_cbranch_execz .LBB0_63
	global_store_dwordx2 v[24:25], v[20:21], off
.LBB0_63:
	s_or_b64 exec, exec, s[0:1]
	ds_read_b128 v[52:55], v102 offset:1024
	ds_read_b128 v[62:65], v102 offset:9216
	v_mul_f32_e32 v20, v40, v36
	v_mul_f32_e32 v21, v38, v36
	v_mul_f32_e32 v16, v16, v36
	v_mul_f32_e32 v17, v17, v36
	s_waitcnt lgkmcnt(0)
	v_fma_f32 v150, v20, v52, v62
	v_fma_f32 v149, v21, v53, v63
	v_fma_f32 v146, v16, v54, v64
	v_fmac_f32_e32 v65, v17, v55
	v_cvt_pk_bf16_f32 v16, v150, v149
	v_cvt_pk_bf16_f32 v17, v146, v65
	s_and_saveexec_b64 s[0:1], s[16:17]
	s_cbranch_execz .LBB0_65
	global_store_dwordx2 v[24:25], v[16:17], off offset:512
.LBB0_65:
	s_or_b64 exec, exec, s[0:1]
	ds_read_b128 v[52:55], v102 offset:2048
	ds_read_b128 v[66:69], v102 offset:10240
	v_mul_f32_e32 v16, v34, v36
	v_mul_f32_e32 v17, v30, v36
	v_mul_f32_e32 v12, v12, v36
	v_mul_f32_e32 v13, v13, v36
	s_waitcnt lgkmcnt(0)
	v_fma_f32 v154, v16, v52, v66
	v_fma_f32 v153, v17, v53, v67
	v_fma_f32 v30, v12, v54, v68
	v_fmac_f32_e32 v69, v13, v55
	v_cvt_pk_bf16_f32 v12, v154, v153
	v_cvt_pk_bf16_f32 v13, v30, v69
	s_and_saveexec_b64 s[0:1], s[16:17]
	s_cbranch_execz .LBB0_67
	global_store_dwordx2 v[24:25], v[12:13], off offset:1024
.LBB0_67:
	s_or_b64 exec, exec, s[0:1]
	ds_read_b128 v[52:55], v102 offset:3072
	ds_read_b128 v[70:73], v102 offset:11264
	v_mul_f32_e32 v12, v32, v36
	v_mul_f32_e32 v13, v28, v36
	v_mul_f32_e32 v4, v4, v36
	v_mul_f32_e32 v5, v5, v36
	s_waitcnt lgkmcnt(0)
	v_fma_f32 v158, v12, v52, v70
	v_fma_f32 v157, v13, v53, v71
	v_fma_f32 v34, v4, v54, v72
	v_fmac_f32_e32 v73, v5, v55
	v_cvt_pk_bf16_f32 v4, v158, v157
	v_cvt_pk_bf16_f32 v5, v34, v73
	s_and_saveexec_b64 s[0:1], s[16:17]
	s_cbranch_execz .LBB0_69
	global_store_dwordx2 v[24:25], v[4:5], off offset:1536
.LBB0_69:
	s_or_b64 exec, exec, s[0:1]
	ds_read_b128 v[52:55], v102 offset:4096
	ds_read_b128 v[74:77], v102 offset:12288
	v_mul_f32_e32 v4, v45, v36
	v_mul_f32_e32 v5, v27, v36
	v_mul_f32_e32 v12, v23, v36
	v_mul_f32_e32 v13, v19, v36
	s_waitcnt lgkmcnt(0)
	v_fma_f32 v162, v4, v52, v74
	v_fma_f32 v161, v5, v53, v75
	v_fma_f32 v38, v12, v54, v76
	v_fmac_f32_e32 v77, v13, v55
	v_cvt_pk_bf16_f32 v4, v162, v161
	v_cvt_pk_bf16_f32 v5, v38, v77
	s_and_saveexec_b64 s[0:1], s[16:17]
	s_cbranch_execz .LBB0_71
	global_store_dwordx2 v[24:25], v[4:5], off offset:2048
.LBB0_71:
	s_or_b64 exec, exec, s[0:1]
	ds_read_b128 v[52:55], v102 offset:5120
	ds_read_b128 v[78:81], v102 offset:13312
	v_mul_f32_e32 v4, v44, v36
	v_mul_f32_e32 v5, v26, v36
	v_mul_f32_e32 v12, v22, v36
	v_mul_f32_e32 v13, v18, v36
	s_waitcnt lgkmcnt(0)
	v_fma_f32 v168, v4, v52, v78
	v_fma_f32 v167, v5, v53, v79
	v_fma_f32 v164, v12, v54, v80
	v_fmac_f32_e32 v81, v13, v55
	v_cvt_pk_bf16_f32 v4, v168, v167
	v_cvt_pk_bf16_f32 v5, v164, v81
	s_and_saveexec_b64 s[0:1], s[16:17]
	s_cbranch_execz .LBB0_73
	global_store_dwordx2 v[24:25], v[4:5], off offset:2560
.LBB0_73:
	s_or_b64 exec, exec, s[0:1]
	ds_read_b128 v[16:19], v102 offset:6144
	ds_read_b128 v[82:85], v102 offset:14336
	v_mul_f32_e32 v4, v15, v36
	v_mul_f32_e32 v5, v11, v36
	v_mul_f32_e32 v9, v9, v36
	v_mul_f32_e32 v3, v3, v36
	s_waitcnt lgkmcnt(0)
	v_fma_f32 v172, v4, v16, v82
	v_fma_f32 v171, v5, v17, v83
	v_fma_f32 v48, v9, v18, v84
	v_fmac_f32_e32 v85, v3, v19
	v_cvt_pk_bf16_f32 v4, v172, v171
	v_cvt_pk_bf16_f32 v5, v48, v85
	s_and_saveexec_b64 s[0:1], s[16:17]
	s_cbranch_execz .LBB0_75
	global_store_dwordx2 v[24:25], v[4:5], off offset:3072
.LBB0_75:
	s_or_b64 exec, exec, s[0:1]
	ds_read_b128 v[16:19], v102 offset:7168
	ds_read_b128 v[86:89], v102 offset:15360
	v_mul_f32_e32 v3, v14, v36
	v_mul_f32_e32 v4, v10, v36
	v_mul_f32_e32 v5, v8, v36
	v_mul_f32_e32 v2, v2, v36
	s_waitcnt lgkmcnt(0)
	v_fma_f32 v178, v3, v16, v86
	v_fma_f32 v177, v4, v17, v87
	v_fma_f32 v174, v5, v18, v88
	v_fmac_f32_e32 v89, v2, v19
	v_cvt_pk_bf16_f32 v2, v178, v177
	v_cvt_pk_bf16_f32 v3, v174, v89
	s_and_saveexec_b64 s[0:1], s[16:17]
	s_cbranch_execz .LBB0_77
	global_store_dwordx2 v[24:25], v[2:3], off offset:3584

.LBB0_82:
	s_or_b64 exec, exec, s[0:1]
	s_waitcnt vmcnt(4)
	v_max_f32_e64 v6, |v55|, |v55|
	v_max_f32_e64 v7, |v54|, |v54|
	v_max_f32_e32 v6, v7, v6
	v_max_f32_e64 v7, |v45|, |v45|
	s_waitcnt lgkmcnt(1)
	v_max_f32_e64 v28, |v44|, |v44|
	v_max_f32_e32 v7, v28, v7
	v_max3_f32 v6, |v52|, |v53|, v6
	v_max3_f32 v7, |v42|, |v43|, v7
	v_max3_f32 v6, v6, 0, v7
	v_max_f32_e64 v7, |v27|, |v27|
	v_max_f32_e64 v28, |v26|, |v26|
	v_max_f32_e32 v7, v28, v7
	v_max_f32_e64 v28, |v23|, |v23|
	s_waitcnt lgkmcnt(0)
	v_max_f32_e64 v29, |v22|, |v22|
	v_max_f32_e32 v28, v29, v28
	v_max3_f32 v7, |v24|, |v25|, v7
	v_max3_f32 v28, |v20|, |v21|, v28
	v_max3_f32 v6, v6, v7, v28
	s_waitcnt vmcnt(3)
	v_max_f32_e64 v7, |v19|, |v19|
	v_max_f32_e64 v28, |v18|, |v18|
	v_max_f32_e32 v7, v28, v7
	v_max_f32_e64 v28, |v15|, |v15|
	v_max_f32_e64 v29, |v14|, |v14|
	v_max_f32_e32 v28, v29, v28
	v_max3_f32 v7, |v16|, |v17|, v7
	v_max3_f32 v28, |v12|, |v13|, v28
	v_max3_f32 v6, v6, v7, v28
	v_max_f32_e64 v7, |v11|, |v11|
	v_max_f32_e64 v28, |v10|, |v10|
	v_max_f32_e32 v7, v28, v7
	v_max_f32_e64 v28, |v5|, |v5|
	v_max_f32_e64 v29, |v4|, |v4|
	v_max_f32_e32 v28, v29, v28
	v_max3_f32 v7, |v8|, |v9|, v7
	v_max3_f32 v28, |v2|, |v3|, v28
	v_max3_f32 v6, v6, v7, v28
	ds_bpermute_b32 v7, v180, v6
	s_waitcnt lgkmcnt(0)
	v_max_f32_e32 v7, v7, v7
	v_max_f32_e32 v6, v6, v7
	ds_bpermute_b32 v7, v181, v6
	s_waitcnt lgkmcnt(0)
	v_max_f32_e32 v7, v7, v7
	v_max_f32_e32 v6, v6, v7
	ds_bpermute_b32 v7, v182, v6
	s_waitcnt lgkmcnt(0)
	v_max_f32_e32 v7, v7, v7
	v_max_f32_e32 v6, v6, v7
	ds_bpermute_b32 v7, v183, v6
	s_waitcnt lgkmcnt(0)
	v_max_f32_e32 v7, v7, v7
	v_max_f32_e32 v6, v6, v7
	ds_bpermute_b32 v7, v184, v6
	s_waitcnt lgkmcnt(0)
	v_max_f32_e32 v7, v7, v7
	v_max_f32_e32 v6, v6, v7
	ds_bpermute_b32 v7, v185, v6
	s_waitcnt lgkmcnt(0)
	v_max_f32_e32 v7, v7, v7
	v_max_f32_e32 v32, v6, v7
	v_cmp_lt_f32_e64 s[0:1], 0, v32
	s_and_saveexec_b64 s[42:43], s[20:21]
	s_xor_b64 s[42:43], exec, s[42:43]
	s_cbranch_execz .LBB0_86
	v_mov_b32_e32 v34, 0
	s_and_saveexec_b64 s[62:63], s[0:1]
	s_cbranch_execz .LBB0_85
	v_div_scale_f32 v6, s[86:87], v32, v32, s82
	v_rcp_f32_e32 v7, v6
	v_div_scale_f32 v28, vcc, s82, v32, s82
	v_fma_f32 v29, -v6, v7, 1.0
	v_fmac_f32_e32 v7, v29, v7
	v_mul_f32_e32 v29, v28, v7
	v_fma_f32 v30, -v6, v29, v28
	v_fmac_f32_e32 v29, v30, v7
	v_fma_f32 v6, -v6, v29, v28
	v_div_fmas_f32 v6, v6, v7, v29
	v_div_fixup_f32 v34, v6, v32, s82

.LBB0_122:
	s_or_b64 exec, exec, s[0:1]
	s_and_saveexec_b64 s[20:21], s[16:17]
	s_cbranch_execz .LBB0_60
	v_mov_b32_e32 v2, s55
	v_mov_b32_e32 v3, s57
	v_cmp_lt_i32_e64 s[16:17], s65, v232
	v_and_b32_e32 v38, 0x3fff, v232
	v_mov_b32_e32 v4, s56
	v_cndmask_b32_e64 v3, v2, v3, s[16:17]
	v_mov_b32_e32 v2, s54
	v_cndmask_b32_e64 v2, v2, v4, s[16:17]
	v_lshlrev_b32_e32 v92, 13, v38
	v_lshl_add_u64 v[2:3], v[2:3], 0, v[92:93]
	v_mov_b32_e32 v117, v93
	v_lshl_add_u64 v[2:3], v[2:3], 0, v[116:117]
	v_add_co_u32_e32 v4, vcc, s61, v2
	global_load_dwordx4 v[32:35], v[2:3], off
	global_load_dwordx4 v[28:31], v[2:3], off offset:16
	global_load_dwordx4 v[22:25], v[2:3], off offset:32
	global_load_dwordx4 v[18:21], v[2:3], off offset:48
	v_addc_co_u32_e32 v5, vcc, 0, v3, vcc
	global_load_dwordx4 v[14:17], v[4:5], off
	v_lshl_add_u64 v[2:3], v[2:3], 0, s[30:31]
	global_load_dwordx4 v[10:13], v[2:3], off offset:16
	global_load_dwordx4 v[6:9], v[2:3], off offset:32
	s_nop 0
	global_load_dwordx4 v[2:5], v[2:3], off offset:48
	v_cmp_gt_i32_e64 s[18:19], s64, v232
	s_waitcnt vmcnt(0)
	v_max_f32_e64 v26, |v35|, |v35|
	v_max_f32_e64 v27, |v34|, |v34|
	s_waitcnt vmcnt(0)
	v_max_f32_e64 v36, |v31|, |v31|
	v_max_f32_e64 v37, |v30|, |v30|
	s_waitcnt vmcnt(0)
	v_max_f32_e64 v39, |v25|, |v25|
	v_max_f32_e64 v40, |v24|, |v24|
	s_waitcnt vmcnt(0)
	v_max_f32_e64 v41, |v21|, |v21|
	v_max_f32_e64 v42, |v20|, |v20|
	v_max_f32_e32 v26, v27, v26
	v_max_f32_e32 v27, v37, v36
	v_max_f32_e32 v36, v40, v39
	v_max_f32_e32 v37, v42, v41
	s_waitcnt vmcnt(0)
	v_max_f32_e64 v39, |v17|, |v17|
	v_max_f32_e64 v40, |v16|, |v16|
	s_waitcnt vmcnt(0)
	v_max_f32_e64 v41, |v13|, |v13|
	v_max_f32_e64 v42, |v12|, |v12|
	v_max3_f32 v26, |v32|, |v33|, v26
	v_max3_f32 v27, |v28|, |v29|, v27
	s_waitcnt vmcnt(0)
	v_max_f32_e64 v43, |v9|, |v9|
	v_max_f32_e64 v44, |v8|, |v8|
	s_waitcnt vmcnt(0)
	v_max_f32_e64 v45, |v5|, |v5|
	v_max_f32_e64 v46, |v4|, |v4|
	v_max3_f32 v36, |v22|, |v23|, v36
	v_max3_f32 v37, |v18|, |v19|, v37
	v_max_f32_e32 v39, v40, v39
	v_max_f32_e32 v40, v42, v41
	v_max3_f32 v26, v26, 0, v27
	v_max_f32_e32 v41, v44, v43
	v_max_f32_e32 v42, v46, v45
	v_max3_f32 v27, |v14|, |v15|, v39
	v_max3_f32 v39, |v10|, |v11|, v40
	v_max3_f32 v26, v26, v36, v37
	v_max3_f32 v40, |v6|, |v7|, v41
	v_max3_f32 v26, v26, v27, v39
	v_max3_f32 v27, |v2|, |v3|, v42
	v_max3_f32 v26, v26, v40, v27
	ds_bpermute_b32 v27, v180, v26
	s_waitcnt lgkmcnt(0)
	v_max_f32_e32 v27, v27, v27
	v_max_f32_e32 v26, v26, v27
	ds_bpermute_b32 v27, v181, v26
	s_waitcnt lgkmcnt(0)
	v_max_f32_e32 v27, v27, v27
	v_max_f32_e32 v26, v26, v27
	ds_bpermute_b32 v27, v182, v26
	s_waitcnt lgkmcnt(0)
	v_max_f32_e32 v27, v27, v27
	v_max_f32_e32 v26, v26, v27
	ds_bpermute_b32 v27, v183, v26
	s_waitcnt lgkmcnt(0)
	v_max_f32_e32 v27, v27, v27
	v_max_f32_e32 v26, v26, v27
	ds_bpermute_b32 v27, v184, v26
	s_waitcnt lgkmcnt(0)
	v_max_f32_e32 v27, v27, v27
	v_max_f32_e32 v26, v26, v27
	ds_bpermute_b32 v27, v185, v26
	s_waitcnt lgkmcnt(0)
	v_max_f32_e32 v27, v27, v27
	v_max_f32_e32 v39, v26, v27
	v_cmp_lt_f32_e64 s[0:1], 0, v39
	s_and_saveexec_b64 s[42:43], s[18:19]
	s_xor_b64 s[42:43], exec, s[42:43]
	s_cbranch_execz .LBB0_127
	v_mov_b32_e32 v41, 0
	s_and_saveexec_b64 s[62:63], s[0:1]
	s_cbranch_execz .LBB0_126
	v_div_scale_f32 v26, s[86:87], v39, v39, s82
	v_rcp_f32_e32 v27, v26
	v_div_scale_f32 v36, vcc, s82, v39, s82
	v_fma_f32 v37, -v26, v27, 1.0
	v_fmac_f32_e32 v27, v37, v27
	v_mul_f32_e32 v37, v36, v27
	v_fma_f32 v40, -v26, v37, v36
	v_fmac_f32_e32 v37, v40, v27
	v_fma_f32 v26, -v26, v37, v36
	v_div_fmas_f32 v26, v26, v27, v37
	v_div_fixup_f32 v41, v26, v39, s82
